# NSA window pass: waves skip tiles past their last query and run only next-tile QK for tiles before their window
# speedup vs baseline: 1.0067x; 1.0067x over previous
.LBB0_702:
	s_add_i32 s4, s18, -1
	s_min_i32 s4, s4, s43
	s_mul_hi_u32 s5, s4, 0xaaaaaaab
	s_lshr_b32 s5, s5, 1
	s_mul_i32 s5, s5, 3
	s_sub_i32 s5, s4, s5
	s_add_i32 s21, s18, -2
	s_lshl_b32 s5, s5, 14
	s_mul_i32 s80, s4, 0x50000
	s_min_i32 s4, s21, s43
	s_add_i32 s23, s5, 0
	s_mul_hi_u32 s5, s4, 0xaaaaaaab
	s_lshr_b32 s5, s5, 1
	s_mul_i32 s5, s5, 3
	s_sub_i32 s5, s4, s5
	s_lshl_b32 s5, s5, 14
	v_lshl_add_u64 v[80:81], v[160:161], 0, s[80:81]
	s_add_i32 m0, s23, s89
	s_add_i32 s22, s5, 0
	s_mul_i32 s4, s4, 0x50000
	s_mov_b32 s5, s81
	global_load_lds_dwordx4 v[80:81], off
	v_lshl_add_u64 v[80:81], v[162:163], 0, s[4:5]
	s_add_i32 s4, s22, s95
	s_add_i32 m0, s4, 0x2000
	s_add_i32 s4, s20, 63
	global_load_lds_dwordx4 v[80:81], off
	s_sub_i32 s5, s20, 31
	s_cmp_gt_i32 s5, s39
	s_cbranch_scc1 .Ltsk702_d1
	s_add_i32 s5, s20, 0x23e
	s_cmp_lt_i32 s5, s39
	s_cbranch_scc1 .Ltsk702_f1
	s_cmp_gt_u32 s4, s39
	s_cselect_b64 s[4:5], -1, 0
	s_cmp_lt_i32 s20, s17
	s_cselect_b64 s[6:7], -1, 0
	s_or_b64 s[4:5], s[4:5], s[6:7]
	s_andn2_b64 vcc, exec, s[4:5]
	s_cbranch_vccnz .LBB0_704
	v_add_u32_e32 v80, 0x7b, v170
	v_add_u32_e32 v81, 0x5b, v170
	v_cmp_gt_u32_e32 vcc, s94, v80
	v_add_u32_e32 v80, 0x7a, v170
	s_nop 0
	v_cndmask_b32_e32 v48, v249, v48, vcc
	v_cmp_gt_u32_e32 vcc, s94, v81
	v_add_u32_e32 v81, 0x5a, v170
	s_nop 0
	v_cndmask_b32_e32 v64, v249, v64, vcc
	v_cmp_gt_u32_e32 vcc, s94, v80
	v_add_u32_e32 v80, 0x79, v170
	s_nop 0
	v_cndmask_b32_e32 v49, v249, v49, vcc
	v_cmp_gt_u32_e32 vcc, s94, v81
	v_add_u32_e32 v81, 0x59, v170
	s_nop 0
	v_cndmask_b32_e32 v65, v249, v65, vcc
	v_cmp_gt_u32_e32 vcc, s94, v80
	v_add_u32_e32 v80, 0x78, v170
	s_nop 0
	v_cndmask_b32_e32 v50, v249, v50, vcc
	v_cmp_gt_u32_e32 vcc, s94, v81
	v_add_u32_e32 v81, 0x58, v170
	s_nop 0
	v_cndmask_b32_e32 v66, v249, v66, vcc
	v_cmp_gt_u32_e32 vcc, s94, v80
	v_add_u32_e32 v80, 0x73, v170
	s_nop 0
	v_cndmask_b32_e32 v51, v249, v51, vcc
	v_cmp_gt_u32_e32 vcc, s94, v81
	v_add_u32_e32 v81, 0x53, v170
	s_nop 0
	v_cndmask_b32_e32 v67, v249, v67, vcc
	v_cmp_gt_u32_e32 vcc, s94, v80
	v_add_u32_e32 v80, 0x72, v170
	s_nop 0
	v_cndmask_b32_e32 v52, v249, v52, vcc
	v_cmp_gt_u32_e32 vcc, s94, v81
	v_add_u32_e32 v81, 0x52, v170
	s_nop 0
	v_cndmask_b32_e32 v68, v249, v68, vcc
	v_cmp_gt_u32_e32 vcc, s94, v80
	v_add_u32_e32 v80, 0x71, v170
	s_nop 0
	v_cndmask_b32_e32 v53, v249, v53, vcc
	v_cmp_gt_u32_e32 vcc, s94, v81
	v_add_u32_e32 v81, 0x51, v170
	s_nop 0
	v_cndmask_b32_e32 v69, v249, v69, vcc
	v_cmp_gt_u32_e32 vcc, s94, v80
	v_add_u32_e32 v80, 0x70, v170
	s_nop 0
	v_cndmask_b32_e32 v54, v249, v54, vcc
	v_cmp_gt_u32_e32 vcc, s94, v81
	v_add_u32_e32 v81, 0x50, v170
	s_nop 0
	v_cndmask_b32_e32 v70, v249, v70, vcc
	v_cmp_gt_u32_e32 vcc, s94, v80
	v_add_u32_e32 v80, 0x6b, v170
	s_nop 0
	v_cndmask_b32_e32 v55, v249, v55, vcc
	v_cmp_gt_u32_e32 vcc, s94, v81
	v_add_u32_e32 v81, 0x4b, v170
	s_nop 0
	v_cndmask_b32_e32 v71, v249, v71, vcc
	v_cmp_gt_u32_e32 vcc, s94, v80
	v_add_u32_e32 v80, 0x6a, v170
	s_nop 0
	v_cndmask_b32_e32 v56, v249, v56, vcc
	v_cmp_gt_u32_e32 vcc, s94, v81
	v_add_u32_e32 v81, 0x4a, v170
	s_nop 0
	v_cndmask_b32_e32 v72, v249, v72, vcc
	v_cmp_gt_u32_e32 vcc, s94, v80
	v_add_u32_e32 v80, 0x69, v170
	s_nop 0
	v_cndmask_b32_e32 v57, v249, v57, vcc
	v_cmp_gt_u32_e32 vcc, s94, v81
	v_add_u32_e32 v81, 0x49, v170
	s_nop 0
	v_cndmask_b32_e32 v73, v249, v73, vcc
	v_cmp_gt_u32_e32 vcc, s94, v80
	v_add_u32_e32 v80, 0x68, v170
	s_nop 0
	v_cndmask_b32_e32 v58, v249, v58, vcc
	v_cmp_gt_u32_e32 vcc, s94, v81
	v_add_u32_e32 v81, 0x48, v170
	s_nop 0
	v_cndmask_b32_e32 v74, v249, v74, vcc
	v_cmp_gt_u32_e32 vcc, s94, v80
	v_add_u32_e32 v80, 0x63, v170
	s_nop 0
	v_cndmask_b32_e32 v59, v249, v59, vcc
	v_cmp_gt_u32_e32 vcc, s94, v81
	v_add_u32_e32 v81, 0x43, v170
	s_nop 0
	v_cndmask_b32_e32 v75, v249, v75, vcc
	v_cmp_gt_u32_e32 vcc, s94, v80
	v_add_u32_e32 v80, 0x62, v170
	s_nop 0
	v_cndmask_b32_e32 v60, v249, v60, vcc
	v_cmp_gt_u32_e32 vcc, s94, v81
	v_add_u32_e32 v81, 0x42, v170
	s_nop 0
	v_cndmask_b32_e32 v76, v249, v76, vcc
	v_cmp_gt_u32_e32 vcc, s94, v80
	v_add_u32_e32 v80, 0x61, v170
	s_nop 0
	v_cndmask_b32_e32 v61, v249, v61, vcc
	v_cmp_gt_u32_e32 vcc, s94, v81
	v_add_u32_e32 v81, 0x41, v170
	s_nop 0
	v_cndmask_b32_e32 v77, v249, v77, vcc
	v_cmp_gt_u32_e32 vcc, s94, v80
	v_add_u32_e32 v80, 0x60, v170
	s_nop 0
	v_cndmask_b32_e32 v62, v249, v62, vcc
	v_cmp_gt_u32_e32 vcc, s94, v81
	v_add_u32_e32 v81, 64, v170
	s_nop 0
	v_cndmask_b32_e32 v78, v249, v78, vcc
	v_cmp_gt_u32_e32 vcc, s94, v80
	s_nop 1
	v_cndmask_b32_e32 v63, v249, v63, vcc
	v_cmp_gt_u32_e32 vcc, s94, v81
	s_nop 1
	v_cndmask_b32_e32 v79, v249, v79, vcc

.Ltsk702_s2:
	s_min_i32 s4, s18, s43
	s_mul_hi_u32 s5, s4, 0xaaaaaaab
	s_lshr_b32 s5, s5, 1
	s_mul_i32 s5, s5, 3
	s_sub_i32 s5, s4, s5
	s_lshl_b32 s6, s5, 14
	s_mul_i32 s4, s4, 0x50000
	s_mov_b32 s5, s81
	v_lshl_add_u64 v[48:49], v[160:161], 0, s[4:5]
	s_add_i32 m0, s61, s6
	s_add_i32 s4, s23, s95
	global_load_lds_dwordx4 v[48:49], off
	v_lshl_add_u64 v[48:49], v[162:163], 0, s[80:81]
	s_add_i32 m0, s4, 0x2000
	s_add_i32 s6, s20, 64
	global_load_lds_dwordx4 v[48:49], off
	s_sub_i32 s5, s6, 31
	s_cmp_gt_i32 s5, s39
	s_cbranch_scc1 .Ltsk702_d2
	s_add_i32 s5, s6, 0x23e
	s_cmp_lt_i32 s5, s39
	s_cbranch_scc1 .Ltsk702_f2
	s_add_i32 s4, s20, 0x7f
	s_cmp_gt_u32 s4, s39
	s_cselect_b64 s[4:5], -1, 0
	s_cmp_lt_i32 s6, s17
	s_cselect_b64 s[6:7], -1, 0
	s_or_b64 s[4:5], s[4:5], s[6:7]
	s_andn2_b64 vcc, exec, s[4:5]
	s_cbranch_vccnz .LBB0_709
	v_add_u32_e32 v48, 59, v170
	v_add_u32_e32 v49, 27, v170
	v_cmp_gt_u32_e32 vcc, s94, v48
	v_add_u32_e32 v48, 58, v170
	s_nop 0
	v_cndmask_b32_e32 v96, v249, v96, vcc
	v_cmp_gt_u32_e32 vcc, s94, v49
	v_add_u32_e32 v49, 26, v170
	s_nop 0
	v_cndmask_b32_e32 v80, v249, v80, vcc
	v_cmp_gt_u32_e32 vcc, s94, v48
	v_add_u32_e32 v48, 57, v170
	s_nop 0
	v_cndmask_b32_e32 v97, v249, v97, vcc
	v_cmp_gt_u32_e32 vcc, s94, v49
	v_add_u32_e32 v49, 25, v170
	s_nop 0
	v_cndmask_b32_e32 v81, v249, v81, vcc
	v_cmp_gt_u32_e32 vcc, s94, v48
	v_add_u32_e32 v48, 56, v170
	s_nop 0
	v_cndmask_b32_e32 v98, v249, v98, vcc
	v_cmp_gt_u32_e32 vcc, s94, v49
	v_add_u32_e32 v49, 24, v170
	s_nop 0
	v_cndmask_b32_e32 v82, v249, v82, vcc
	v_cmp_gt_u32_e32 vcc, s94, v48
	v_add_u32_e32 v48, 51, v170
	s_nop 0
	v_cndmask_b32_e32 v99, v249, v99, vcc
	v_cmp_gt_u32_e32 vcc, s94, v49
	v_add_u32_e32 v49, 19, v170
	s_nop 0
	v_cndmask_b32_e32 v83, v249, v83, vcc
	v_cmp_gt_u32_e32 vcc, s94, v48
	v_add_u32_e32 v48, 50, v170
	s_nop 0
	v_cndmask_b32_e32 v100, v249, v100, vcc
	v_cmp_gt_u32_e32 vcc, s94, v49
	v_add_u32_e32 v49, 18, v170
	s_nop 0
	v_cndmask_b32_e32 v84, v249, v84, vcc
	v_cmp_gt_u32_e32 vcc, s94, v48
	v_add_u32_e32 v48, 49, v170
	s_nop 0
	v_cndmask_b32_e32 v101, v249, v101, vcc
	v_cmp_gt_u32_e32 vcc, s94, v49
	v_add_u32_e32 v49, 17, v170
	s_nop 0
	v_cndmask_b32_e32 v85, v249, v85, vcc
	v_cmp_gt_u32_e32 vcc, s94, v48
	v_add_u32_e32 v48, 48, v170
	s_nop 0
	v_cndmask_b32_e32 v102, v249, v102, vcc
	v_cmp_gt_u32_e32 vcc, s94, v49
	v_add_u32_e32 v49, 16, v170
	s_nop 0
	v_cndmask_b32_e32 v86, v249, v86, vcc
	v_cmp_gt_u32_e32 vcc, s94, v48
	v_add_u32_e32 v48, 43, v170
	s_nop 0
	v_cndmask_b32_e32 v103, v249, v103, vcc
	v_cmp_gt_u32_e32 vcc, s94, v49
	v_add_u32_e32 v49, 11, v170
	s_nop 0
	v_cndmask_b32_e32 v87, v249, v87, vcc
	v_cmp_gt_u32_e32 vcc, s94, v48
	v_add_u32_e32 v48, 42, v170
	s_nop 0
	v_cndmask_b32_e32 v104, v249, v104, vcc
	v_cmp_gt_u32_e32 vcc, s94, v49
	v_add_u32_e32 v49, 10, v170
	s_nop 0
	v_cndmask_b32_e32 v88, v249, v88, vcc
	v_cmp_gt_u32_e32 vcc, s94, v48
	v_add_u32_e32 v48, 41, v170
	s_nop 0
	v_cndmask_b32_e32 v105, v249, v105, vcc
	v_cmp_gt_u32_e32 vcc, s94, v49
	v_add_u32_e32 v49, 9, v170
	s_nop 0
	v_cndmask_b32_e32 v89, v249, v89, vcc
	v_cmp_gt_u32_e32 vcc, s94, v48
	v_add_u32_e32 v48, 40, v170
	s_nop 0
	v_cndmask_b32_e32 v106, v249, v106, vcc
	v_cmp_gt_u32_e32 vcc, s94, v49
	v_add_u32_e32 v49, 8, v170
	s_nop 0
	v_cndmask_b32_e32 v90, v249, v90, vcc
	v_cmp_gt_u32_e32 vcc, s94, v48
	v_add_u32_e32 v48, 35, v170
	s_nop 0
	v_cndmask_b32_e32 v107, v249, v107, vcc
	v_cmp_gt_u32_e32 vcc, s94, v49
	v_add_u32_e32 v49, 3, v170
	s_nop 0
	v_cndmask_b32_e32 v91, v249, v91, vcc
	v_cmp_gt_u32_e32 vcc, s94, v48
	v_add_u32_e32 v48, 34, v170
	s_nop 0
	v_cndmask_b32_e32 v108, v249, v108, vcc
	v_cmp_gt_u32_e32 vcc, s94, v49
	v_add_u32_e32 v49, 2, v170
	s_nop 0
	v_cndmask_b32_e32 v92, v249, v92, vcc
	v_cmp_gt_u32_e32 vcc, s94, v48
	v_add_u32_e32 v48, 33, v170
	s_nop 0
	v_cndmask_b32_e32 v109, v249, v109, vcc
	v_cmp_gt_u32_e32 vcc, s94, v49
	v_add_u32_e32 v49, 1, v170
	s_nop 0
	v_cndmask_b32_e32 v93, v249, v93, vcc
	v_cmp_gt_u32_e32 vcc, s94, v48
	v_add_u32_e32 v48, 32, v170
	s_nop 0
	v_cndmask_b32_e32 v110, v249, v110, vcc
	v_cmp_gt_u32_e32 vcc, s94, v49
	s_nop 1
	v_cndmask_b32_e32 v94, v249, v94, vcc
	v_cmp_gt_u32_e32 vcc, s94, v48
	s_nop 1
	v_cndmask_b32_e32 v111, v249, v111, vcc
	v_cmp_gt_u32_e32 vcc, s94, v170
	s_nop 1
	v_cndmask_b32_e32 v95, v249, v95, vcc

; template <int DQK, int MODE> ...
;     ...
;     for (int kt = kt_lo; kt <= kt_hi; kt += 2) {
;         AT_STEPF(pa0, pa1, pb0, pb1, kt);
;         if (kt + 1 <= kt_hi) AT_STEPF(pb0, pb1, pa0, pa1, kt + 1);
;     }
.Ltsk702_d1:
	s_waitcnt vmcnt(2) lgkmcnt(0)
	s_barrier
	s_add_i32 s4, s18, -4
	s_cmp_ge_u32 s4, s43
	s_cbranch_scc1 .LBB0_701
	s_branch .Ltsk702_s2
.Ltsk702_f1:
	s_add_i32 s4, s18, -3
	s_min_i32 s4, s4, s43
	s_mul_hi_u32 s5, s4, 0xaaaaaaab
	s_lshr_b32 s5, s5, 1
	s_mul_i32 s5, s5, 3
	s_sub_i32 s4, s4, s5
	v_lshl_add_u32 v84, s4, 14, v168
	ds_read_b128 v[80:83], v84
	ds_read_b128 v[152:155], v84 offset:512
	ds_read_b128 v[148:151], v84 offset:2048
	ds_read_b128 v[136:139], v84 offset:2560
	ds_read_b128 v[144:147], v84 offset:4096
	ds_read_b128 v[132:135], v84 offset:4608
	ds_read_b128 v[140:143], v84 offset:6144
	ds_read_b128 v[128:131], v84 offset:6656
	s_waitcnt lgkmcnt(0)
	v_mfma_f32_32x32x16_bf16 v[96:111], v[80:83], v[112:115], v[32:47]
	v_mfma_f32_32x32x16_bf16 v[80:95], v[152:155], v[112:115], v[32:47]
	v_mfma_f32_32x32x16_bf16 v[96:111], v[148:151], v[116:119], v[96:111]
	v_mfma_f32_32x32x16_bf16 v[96:111], v[144:147], v[120:123], v[96:111]
	v_mfma_f32_32x32x16_bf16 v[80:95], v[136:139], v[116:119], v[80:95]
	v_mfma_f32_32x32x16_bf16 v[96:111], v[140:143], v[124:127], v[96:111]
	v_mfma_f32_32x32x16_bf16 v[80:95], v[132:135], v[120:123], v[80:95]
	s_waitcnt vmcnt(2) lgkmcnt(0)
	s_barrier
	v_mfma_f32_32x32x16_bf16 v[80:95], v[128:131], v[124:127], v[80:95]
	s_add_i32 s4, s18, -4
	s_cmp_ge_u32 s4, s43
	s_cbranch_scc1 .LBB0_701
	s_branch .Ltsk702_s2

; template <int DQK, int MODE> ...
;     ...
;     for (int kt = kt_lo; kt <= kt_hi; kt += 2) {
;         AT_STEPF(pa0, pa1, pb0, pb1, kt);
;         if (kt + 1 <= kt_hi) AT_STEPF(pb0, pb1, pa0, pa1, kt + 1);
.Ltsk702_f2:
	v_add3_u32 v48, s22, v166, v167
	ds_read_b128 v[64:67], v48
	ds_read_b128 v[152:155], v48 offset:512
	ds_read_b128 v[140:143], v48 offset:2048
	ds_read_b128 v[132:135], v48 offset:2560
	ds_read_b128 v[144:147], v48 offset:4096
	ds_read_b128 v[136:139], v48 offset:4608
	ds_read_b128 v[148:151], v48 offset:6144
	ds_read_b128 v[128:131], v48 offset:6656
	s_waitcnt lgkmcnt(0)
	v_mfma_f32_32x32x16_bf16 v[48:63], v[64:67], v[112:115], v[32:47]
	v_mfma_f32_32x32x16_bf16 v[64:79], v[152:155], v[112:115], v[32:47]
	v_mfma_f32_32x32x16_bf16 v[48:63], v[140:143], v[116:119], v[48:63]
	v_mfma_f32_32x32x16_bf16 v[48:63], v[144:147], v[120:123], v[48:63]
	v_mfma_f32_32x32x16_bf16 v[64:79], v[132:135], v[116:119], v[64:79]
	v_mfma_f32_32x32x16_bf16 v[48:63], v[148:151], v[124:127], v[48:63]
	v_mfma_f32_32x32x16_bf16 v[64:79], v[136:139], v[120:123], v[64:79]
	s_waitcnt vmcnt(2) lgkmcnt(0)
	s_barrier
	v_mfma_f32_32x32x16_bf16 v[64:79], v[128:131], v[124:127], v[64:79]
	s_branch .LBB0_701
